# attention main loop: next K/V tile prefetched during PV phase (was loaded at loop top with no overlap)
# speedup vs baseline: 1.0048x; 1.0048x over previous
; __device__ __forceinline__ int tid_() { int t = threadIdx.x; asm volatile("" : "+v"(t)); return t; }
; __device__ __forceinline__ void attn_item(CParams& p, int j2, int b, int h, int q0row, int nkeys, bf16_t* smem) {
;     const int tid = tid_(), lane = tid & 63, wave = tid >> 6, l16 = lane & 15, quad = lane >> 4;
;     const int kh = h >> 2;
;     const bf16_t* Q = (const bf16_t*)(p.ws + WS_Q);
;     const bf16_t* Kb = (const bf16_t*)(p.ws + WS_K) + (size_t)b * TALL * 128 + kh * 64;
;     const bf16_t* Vb = (const bf16_t*)(p.ws + WS_VT) + (size_t)(b * 2 + kh) * 64 * TALL;
;     bf16_t* sK = smem; bf16_t* sV = smem + 64 * GST;
;     constexpr float LOG2E = 1.4426950408889634f;
;     float mb;
;     {
;         float gq = fabsf(p.q_norm_g[j2 * 64 + lane]), gk = fabsf(p.k_norm_g[j2 * 64 + lane]);
; #pragma unroll
;         for (int o = 1; o < 64; o <<= 1) { gq = fmaxf(gq, __shfl_xor(gq, o)); gk = fmaxf(gk, __shfl_xor(gk, o)); }
;         mb = 8.f * 1.02f * gq * gk * LOG2E;
;     }
;     bf16x8 qf[4][2];
; #pragma unroll
;     for (int i = 0; i < 4; ++i)
; #pragma unroll
;         for (int ks = 0; ks < 2; ++ks)
;             qf[i][ks] = *(const bf16x8*)(Q + (size_t)(q0row + wave * 64 + i * 16 + l16) * 512 + h * 64 + ks * 32 + quad * 8);
;     f32x4 o[5][4];
; #pragma unroll
;     for (int d = 0; d < 5; ++d)
; #pragma unroll
;         for (int i = 0; i < 4; ++i) o[d][i] = (f32x4){0.f, 0.f, 0.f, 0.f};
;     lds_sync();
;     {
;         const int r = 64 + (tid >> 4);
;         u32x2 one; one.x = r == 64 ? 0x3F803F80u : 0u; one.y = one.x;
;         *(u32x2*)(sV + r * GST + (tid & 15) * 4) = one;
;     }
.LBB0_178:
	s_waitcnt vmcnt(20)
	v_mov_b32_e32 v20, v167
	v_cmp_lt_i32_e32 vcc, v200, v199
	v_and_b32_e32 v0, 63, v20
	v_or_b32_e32 v164, s14, v0
	v_lshlrev_b64 v[0:1], 2, v[164:165]
	v_lshl_add_u64 v[2:3], s[44:45], 0, v[0:1]
	v_lshl_add_u64 v[0:1], s[46:47], 0, v[0:1]
	global_load_dword v10, v[2:3], off
	global_load_dword v11, v[0:1], off
	s_lshl_b32 s4, s24, 1
	v_cndmask_b32_e32 v0, v197, v200, vcc
	s_ashr_i32 s5, s24, 8
	s_and_b32 s4, s4, 14
	s_waitcnt vmcnt(21)
	v_lshlrev_b32_e32 v12, 2, v0
	s_add_i32 s4, s4, s5
	s_lshl_b32 s6, s24, 5
	s_ashr_i32 s7, s4, 3
	v_cmp_lt_i32_e32 vcc, v201, v199
	s_and_b32 s6, s6, 0x1f00
	s_and_b32 s8, s4, 7
	s_bfe_u32 s25, s4, 0x10002
	s_lshl_b32 s4, s7, 13
	v_cndmask_b32_e32 v1, v197, v201, vcc
	s_mul_i32 s26, s7, 0x210000
	s_or_b32 s4, s4, s6
	v_lshlrev_b32_e32 v13, 2, v1
	v_and_b32_e32 v1, 0xffffffc0, v20
	s_mul_hi_i32 s5, s7, 0x210000
	s_add_u32 s6, s12, s26
	v_add_u32_e32 v219, s4, v1
	s_addc_u32 s5, s13, s5
	s_lshl_b32 s4, s25, 7
	v_cmp_lt_i32_e32 vcc, v202, v199
	s_add_u32 s4, s6, s4
	v_and_b32_e32 v220, 15, v20
	v_cndmask_b32_e32 v2, v197, v202, vcc
	v_cmp_lt_i32_e32 vcc, v203, v199
	v_bfe_u32 v0, v20, 4, 2
	s_addc_u32 s5, s5, 0
	s_lshl_b32 s6, s7, 1
	v_cndmask_b32_e32 v3, v197, v203, vcc
	v_cmp_lt_i32_e32 vcc, v204, v199
	v_lshlrev_b32_e32 v169, 3, v0
	v_or_b32_e32 v0, v219, v220
	s_lshl_b32 s7, s8, 7
	s_or_b32 s6, s25, s6
	v_cndmask_b32_e32 v4, v197, v204, vcc
	v_cmp_lt_i32_e32 vcc, v205, v199
	v_or_b32_e32 v172, 32, v0
	s_mul_hi_i32 s25, s6, 0x108000
	s_mul_i32 s26, s6, 0x108000
	s_add_u32 s6, s15, s7
	v_cndmask_b32_e32 v5, v197, v205, vcc
	v_and_b32_e32 v164, 48, v20
	s_waitcnt vmcnt(11)
	v_ashrrev_i32_e32 v173, 31, v172
	s_addc_u32 s7, s16, 0
	v_lshlrev_b32_e32 v21, 2, v4
	v_lshlrev_b32_e32 v22, 2, v5
	v_lshlrev_b64 v[4:5], 10, v[172:173]
	v_lshl_add_u64 v[8:9], s[6:7], 0, v[164:165]
	v_lshlrev_b32_e32 v14, 2, v2
	v_ashrrev_i32_e32 v1, 31, v0
	v_or_b32_e32 v174, 16, v0
	v_or_b32_e32 v170, 48, v0
	v_lshlrev_b64 v[0:1], 10, v[0:1]
	s_waitcnt vmcnt(10)
	v_ashrrev_i32_e32 v175, 31, v174
	v_ashrrev_i32_e32 v171, 31, v170
	v_lshlrev_b32_e32 v15, 2, v3
	v_lshlrev_b64 v[2:3], 10, v[174:175]
	v_lshlrev_b64 v[6:7], 10, v[170:171]
	v_lshl_add_u64 v[0:1], v[8:9], 0, v[0:1]
	v_lshl_add_u64 v[2:3], v[8:9], 0, v[2:3]
	v_lshl_add_u64 v[18:19], v[8:9], 0, v[6:7]
	v_cmp_gt_u32_e32 vcc, 16, v20
	s_movk_i32 s2, 0x90
	s_add_u32 s6, s17, s26
	s_addc_u32 s7, s18, s25
	v_ashrrev_i32_e32 v176, 3, v20
	v_ashrrev_i32_e32 v177, 31, v176
	v_add_u32_e32 v186, 32, v176
	s_mov_b32 s9, 0
	v_ashrrev_i32_e32 v187, 31, v186
	s_movk_i32 s10, 0x90
	v_mov_b64_e32 v[188:189], v[176:177]
	s_waitcnt vmcnt(1)
	v_and_b32_e32 v16, 0x7fffffff, v10
	s_waitcnt vmcnt(0)
	v_and_b32_e32 v17, 0x7fffffff, v11
	ds_bpermute_b32 v16, v12, v16
	ds_bpermute_b32 v12, v12, v17
	v_max_f32_e64 v10, |v10|, |v10|
	v_max_f32_e64 v11, |v11|, |v11|
	s_waitcnt lgkmcnt(1)
	v_max_f32_e32 v16, v16, v16
	s_waitcnt lgkmcnt(0)
	v_max_f32_e32 v12, v12, v12
	v_max_f32_e32 v10, v10, v16
	v_max_f32_e32 v11, v11, v12
	ds_bpermute_b32 v12, v13, v10
	ds_bpermute_b32 v13, v13, v11
	v_lshl_add_u64 v[16:17], v[8:9], 0, v[4:5]
	s_waitcnt lgkmcnt(1)
	v_max_f32_e32 v4, v12, v12
	s_waitcnt lgkmcnt(0)
	v_max_f32_e32 v5, v13, v13
	v_max_f32_e32 v12, v10, v4
	v_max_f32_e32 v13, v11, v5
	ds_bpermute_b32 v23, v14, v12
	ds_bpermute_b32 v14, v14, v13
	global_load_dwordx4 v[4:7], v[0:1], off
	global_load_dwordx4 v[8:11], v[0:1], off offset:64
	s_waitcnt lgkmcnt(1)
	v_max_f32_e32 v0, v23, v23
	s_waitcnt lgkmcnt(0)
	v_max_f32_e32 v1, v14, v14
	v_max_f32_e32 v1, v13, v1
	ds_bpermute_b32 v36, v15, v1
	v_max_f32_e32 v0, v12, v0
	ds_bpermute_b32 v23, v15, v0
	global_load_dwordx4 v[12:15], v[2:3], off
	global_load_dwordx4 v[24:27], v[2:3], off offset:64
	global_load_dwordx4 v[28:31], v[16:17], off
	global_load_dwordx4 v[32:35], v[16:17], off offset:64
	s_waitcnt lgkmcnt(1)
	v_max_f32_e32 v3, v36, v36
	global_load_dwordx4 v[36:39], v[18:19], off
	global_load_dwordx4 v[40:43], v[18:19], off offset:64
	s_waitcnt lgkmcnt(0)
	v_max_f32_e32 v2, v23, v23
	v_max_f32_e32 v1, v1, v3
	v_max_f32_e32 v0, v0, v2
	ds_bpermute_b32 v3, v21, v1
	ds_bpermute_b32 v2, v21, v0
	v_lshrrev_b32_e32 v18, 4, v20
	v_lshlrev_b32_e32 v19, 3, v20
	v_mul_lo_u32 v18, v18, s2
	s_waitcnt lgkmcnt(1)
	v_max_f32_e32 v3, v3, v3
	s_waitcnt lgkmcnt(0)
	v_max_f32_e32 v2, v2, v2
	v_max_f32_e32 v3, v1, v3
	v_max_f32_e32 v2, v0, v2
	ds_bpermute_b32 v17, v22, v3
	ds_bpermute_b32 v16, v22, v2
	v_cndmask_b32_e32 v0, 0, v215, vcc
	v_and_b32_e32 v19, 0x78, v19
	v_mov_b32_e32 v1, v0
	v_add3_u32 v18, 0, v18, v19
	s_waitcnt lgkmcnt(0)
	s_barrier
; __device__ __forceinline__ f32x4 mfma16(bf16x8 a, bf16x8 b, f32x4 c) { return __builtin_amdgcn_mfma_f32_16x16x32_bf16(a, b, c, 0, 0, 0); }
; __device__ __forceinline__ void attn_item(CParams& p, int j2, int b, int h, int q0row, int nkeys, bf16_t* smem) {
;     ...
;     f32x4 o[5][4];
; #pragma unroll
;     for (int d = 0; d < 5; ++d)
; #pragma unroll
;         for (int i = 0; i < 4; ++i) o[d][i] = (f32x4){0.f, 0.f, 0.f, 0.f};
;     lds_sync();
;     {
;         const int r = 64 + (tid >> 4);
;         u32x2 one; one.x = r == 64 ? 0x3F803F80u : 0u; one.y = one.x;
;         *(u32x2*)(sV + r * GST + (tid & 15) * 4) = one;
;     }
;     const int srow = tid >> 3, skc = (tid & 7) * 8;
;     u32x4 rk[2], rv[2];
; #pragma unroll
;     for (int i = 0; i < 2; ++i) {
;         rk[i] = *(const u32x4*)(Kb + (size_t)(srow + i * 32) * 128 + skc);
;         rv[i] = *(const u32x4*)(Vb + (size_t)(srow + i * 32) * TALL + skc);
;     }
;     const int nt = nkeys >> 6;
; #pragma unroll 1
;     for (int kt = 0; kt < nt; ++kt) {
;         lds_sync();
; #pragma unroll
;         for (int i = 0; i < 2; ++i) {
;             *(u32x4*)(sK + (srow + i * 32) * GST + skc) = rk[i];
;             *(u32x4*)(sV + (srow + i * 32) * GST + skc) = rv[i];
;         }
;         lds_sync();
;         {
;             const int t0 = (kt + 1 < nt ? kt + 1 : kt) << 6;
; #pragma unroll
;             for (int i = 0; i < 2; ++i) {
;                 rk[i] = *(const u32x4*)(Kb + (size_t)(t0 + srow + i * 32) * 128 + skc);
;                 rv[i] = *(const u32x4*)(Vb + (size_t)(srow + i * 32) * TALL + t0 + skc);
;             }
;         }
;         bf16x8 pf[2][4];
; #pragma unroll
;         for (int ih = 0; ih < 2; ++ih) {
;             f32x4 s[4][2];
; #pragma unroll
;             for (int tt = 0; tt < 4; ++tt)
; #pragma unroll
;                 for (int i = 0; i < 2; ++i) s[tt][i] = (f32x4){-mb, -mb, -mb, -mb};
; #pragma unroll
;             for (int ks = 0; ks < 2; ++ks)
; #pragma unroll
;                 for (int tt = 0; tt < 4; ++tt) {
;                     const bf16x8 kf = lds16(sK + (tt * 16 + l16) * GST + ks * 32 + quad * 8);
; #pragma unroll
;                     for (int i = 0; i < 2; ++i) s[tt][i] = mfma16(kf, qf[ih * 2 + i][ks], s[tt][i]);
	ds_write_b64 v18, v[0:1] offset:18432
	v_lshlrev_b32_e32 v0, 4, v20
	v_and_b32_e32 v0, 0x70, v0
	v_mov_b32_e32 v1, v165
	v_lshl_add_u64 v[178:179], s[4:5], 0, v[0:1]
	v_lshl_add_u64 v[180:181], s[6:7], 0, v[0:1]
	v_max_f32_e32 v1, v17, v17
	v_max_f32_e32 v1, v3, v1
	v_max_f32_e32 v3, v16, v16
	v_max_f32_e32 v2, v2, v3
	v_mul_f32_e32 v2, 0x41028f5c, v2
	v_mul_f32_e32 v1, v1, v2
	v_mul_lo_u32 v3, v176, s2
	v_mul_f32_e32 v44, 0xbfb8aa3b, v1
	v_add_u32_e32 v1, 0, v164
	v_add_u32_e32 v2, 0, v169
	v_add3_u32 v164, 0, v0, v3
	v_mul_u32_u24_e32 v3, 0x90, v220
	v_mov_b32_e32 v0, 0
	v_mad_i64_i32 v[182:183], s[4:5], v176, s31, 0
	v_mad_i64_i32 v[184:185], s[4:5], v186, s31, 0
	v_mov_b32_e32 v45, v44
	v_mov_b32_e32 v46, v44
	v_mov_b32_e32 v47, v44
	v_add_u32_e32 v171, v1, v3
	v_add_u32_e32 v173, v2, v3
	v_mov_b64_e32 v[190:191], v[180:181]
	v_mov_b32_e32 v1, v0
	v_mov_b32_e32 v2, v0
	v_mov_b32_e32 v3, v0
	v_mov_b32_e32 v52, v0
	v_mov_b32_e32 v53, v0
	v_mov_b32_e32 v54, v0
	v_mov_b32_e32 v55, v0
	v_mov_b32_e32 v68, v0
	v_mov_b32_e32 v69, v0
	v_mov_b32_e32 v70, v0
	v_mov_b32_e32 v71, v0
	v_mov_b32_e32 v88, v0
	v_mov_b32_e32 v89, v0
	v_mov_b32_e32 v90, v0
	v_mov_b32_e32 v91, v0
	v_mov_b32_e32 v20, v0
	v_mov_b32_e32 v21, v0
	v_mov_b32_e32 v22, v0
	v_mov_b32_e32 v23, v0
	v_mov_b32_e32 v60, v0
	v_mov_b32_e32 v61, v0
	v_mov_b32_e32 v62, v0
	v_mov_b32_e32 v63, v0
	v_mov_b32_e32 v76, v0
	v_mov_b32_e32 v77, v0
	v_mov_b32_e32 v78, v0
	v_mov_b32_e32 v79, v0
	v_mov_b32_e32 v96, v0
	v_mov_b32_e32 v97, v0
	v_mov_b32_e32 v98, v0
	v_mov_b32_e32 v99, v0
	v_mov_b32_e32 v80, v0
	v_mov_b32_e32 v81, v0
	v_mov_b32_e32 v82, v0
	v_mov_b32_e32 v83, v0
	v_mov_b32_e32 v100, v0
	v_mov_b32_e32 v101, v0
	v_mov_b32_e32 v102, v0
	v_mov_b32_e32 v103, v0
	v_mov_b32_e32 v108, v0
	v_mov_b32_e32 v109, v0
	v_mov_b32_e32 v110, v0
	v_mov_b32_e32 v111, v0
	v_mov_b32_e32 v112, v0
	v_mov_b32_e32 v113, v0
	v_mov_b32_e32 v114, v0
	v_mov_b32_e32 v115, v0
	v_mov_b32_e32 v92, v0
	v_mov_b32_e32 v93, v0
	v_mov_b32_e32 v94, v0
	v_mov_b32_e32 v95, v0
	v_mov_b32_e32 v72, v0
	v_mov_b32_e32 v73, v0
	v_mov_b32_e32 v74, v0
	v_mov_b32_e32 v75, v0
	v_mov_b32_e32 v56, v0
	v_mov_b32_e32 v57, v0
	v_mov_b32_e32 v58, v0
	v_mov_b32_e32 v59, v0
	v_mov_b32_e32 v16, v0
	v_mov_b32_e32 v17, v0
	v_mov_b32_e32 v18, v0
	v_mov_b32_e32 v19, v0
	v_mov_b32_e32 v104, v0
	v_mov_b32_e32 v105, v0
	v_mov_b32_e32 v106, v0
	v_mov_b32_e32 v107, v0
	v_mov_b32_e32 v84, v0
	v_mov_b32_e32 v85, v0
	v_mov_b32_e32 v86, v0
	v_mov_b32_e32 v87, v0
	v_mov_b32_e32 v64, v0
	v_mov_b32_e32 v65, v0
	v_mov_b32_e32 v66, v0
	v_mov_b32_e32 v67, v0
	v_mov_b32_e32 v48, v0
	v_mov_b32_e32 v49, v0
	v_mov_b32_e32 v50, v0
	v_mov_b32_e32 v51, v0
	v_lshlrev_b64 v[222:223], 8, v[188:189]
	v_lshl_add_u64 v[222:223], v[178:179], 0, v[222:223]
	v_lshl_add_u64 v[226:227], v[190:191], 0, v[182:183]
	global_load_dwordx4 v[222:225], v[222:223], off
	v_lshlrev_b64 v[230:231], 8, v[186:187]
	global_load_dwordx4 v[226:229], v[226:227], off
	v_lshl_add_u64 v[230:231], v[178:179], 0, v[230:231]
	v_lshl_add_u64 v[234:235], v[190:191], 0, v[184:185]
	global_load_dwordx4 v[230:233], v[230:231], off
	global_load_dwordx4 v[234:237], v[234:235], off
.LBB0_179:
	s_add_i32 s4, s9, 1
	s_waitcnt lgkmcnt(0)
	s_barrier
	s_cmpk_lt_u32 s9, 0x83
	s_cselect_b32 s5, s4, s9
	s_lshl_b32 s6, s5, 6
	v_add_u32_e32 v188, s6, v176
	s_ashr_i32 s7, s6, 31
	v_add_u32_e32 v186, 32, v188
	v_lshl_add_u64 v[190:191], s[6:7], 1, v[180:181]
	v_ashrrev_i32_e32 v189, 31, v188
	v_ashrrev_i32_e32 v187, 31, v186
	s_cmpk_lg_i32 s4, 0x84
	s_mov_b32 s9, s4
	s_waitcnt vmcnt(3)
	ds_write_b128 v164, v[222:225]
	s_waitcnt vmcnt(2)
	ds_write_b128 v164, v[226:229] offset:9216
	s_waitcnt vmcnt(1)
	ds_write_b128 v164, v[230:233] offset:4608
	s_waitcnt vmcnt(0)
	ds_write_b128 v164, v[234:237] offset:13824
	s_waitcnt lgkmcnt(0)
	s_barrier
	ds_read_b128 v[148:151], v171 offset:4608
	ds_read_b128 v[156:159], v171 offset:4672
	ds_read_b128 v[136:139], v171
	ds_read_b128 v[132:135], v171 offset:64
	s_waitcnt lgkmcnt(3)
	v_mfma_f32_16x16x32_bf16 v[160:163], v[148:151], v[4:7], v[44:47]
	ds_read_b128 v[152:155], v171 offset:6912
	ds_read_b128 v[140:143], v171 offset:2304
	ds_read_b128 v[144:147], v171 offset:2368
	s_waitcnt lgkmcnt(5)
	v_mfma_f32_16x16x32_bf16 v[234:237], v[156:159], v[8:11], v[160:163]
	s_nop 2
	ds_read_b128 v[160:163], v171 offset:6976
	s_waitcnt lgkmcnt(5)
	v_mfma_f32_16x16x32_bf16 v[116:119], v[136:139], v[4:7], v[44:47]
	s_nop 1
	v_exp_f32_e32 v234, v234
	v_exp_f32_e32 v235, v235
	v_exp_f32_e32 v236, v236
	s_waitcnt lgkmcnt(3)
	v_mfma_f32_16x16x32_bf16 v[226:229], v[152:155], v[4:7], v[44:47]
	v_exp_f32_e32 v237, v237
	v_mfma_f32_16x16x32_bf16 v[120:123], v[136:139], v[12:15], v[44:47]
	s_waitcnt lgkmcnt(2)
	v_mfma_f32_16x16x32_bf16 v[124:127], v[140:143], v[4:7], v[44:47]
	v_mfma_f32_16x16x32_bf16 v[222:225], v[148:151], v[12:15], v[44:47]
	v_mfma_f32_16x16x32_bf16 v[230:233], v[152:155], v[12:15], v[44:47]
	v_mfma_f32_16x16x32_bf16 v[116:119], v[132:135], v[8:11], v[116:119]
	s_waitcnt lgkmcnt(0)
; __device__ __forceinline__ f32x4 mfma16(bf16x8 a, bf16x8 b, f32x4 c) { return __builtin_amdgcn_mfma_f32_16x16x32_bf16(a, b, c, 0, 0, 0); }
; __device__ __forceinline__ void attn_item(CParams& p, int j2, int b, int h, int q0row, int nkeys, bf16_t* smem) {
;     ...
;         {
;             const int t0 = (kt + 1 < nt ? kt + 1 : kt) << 6;
; #pragma unroll
;             for (int i = 0; i < 2; ++i) {
;                 rk[i] = *(const u32x4*)(Kb + (size_t)(t0 + srow + i * 32) * 128 + skc);
;                 rv[i] = *(const u32x4*)(Vb + (size_t)(srow + i * 32) * TALL + t0 + skc);
;             }
;         }
;         bf16x8 pf[2][4];
; #pragma unroll
;         for (int ih = 0; ih < 2; ++ih) {
;             f32x4 s[4][2];
; #pragma unroll
;             for (int tt = 0; tt < 4; ++tt)
; #pragma unroll
;                 for (int i = 0; i < 2; ++i) s[tt][i] = (f32x4){-mb, -mb, -mb, -mb};
; #pragma unroll
;             for (int ks = 0; ks < 2; ++ks)
; #pragma unroll
;                 for (int tt = 0; tt < 4; ++tt) {
;                     const bf16x8 kf = lds16(sK + (tt * 16 + l16) * GST + ks * 32 + quad * 8);
; #pragma unroll
;                     for (int i = 0; i < 2; ++i) s[tt][i] = mfma16(kf, qf[ih * 2 + i][ks], s[tt][i]);
;                 }
; #pragma unroll
;             for (int i = 0; i < 2; ++i) {
; #pragma unroll
;                 for (int tt = 0; tt < 4; ++tt) {
; #pragma unroll
;                     for (int r = 0; r < 4; ++r) s[tt][i][r] = __builtin_amdgcn_exp2f(s[tt][i][r]);
;                 }
; #pragma unroll
;                 for (int ksp = 0; ksp < 2; ++ksp) pf[ksp][ih * 2 + i] = pack8(s[2 * ksp][i], s[2 * ksp + 1][i]);
;             }
;         }
; #pragma unroll
;         for (int ksp = 0; ksp < 2; ++ksp)
; #pragma unroll
;             for (int d = 0; d < 5; ++d) {
;                 const bf16_t* vp = sV + (d * 16 + l16) * GST + ksp * 32 + quad * 4;
;                 const bf16x8 vf = lds8x2(vp, vp + 16);
; #pragma unroll
;                 for (int i = 0; i < 4; ++i) o[d][i] = mfma16(vf, pf[ksp][i], o[d][i]);
	v_mfma_f32_16x16x32_bf16 v[226:229], v[160:163], v[8:11], v[226:229]
	v_mfma_f32_16x16x32_bf16 v[128:131], v[140:143], v[12:15], v[44:47]
	s_nop 4
	v_exp_f32_e32 v118, v118
	v_exp_f32_e32 v119, v119
	v_exp_f32_e32 v226, v226
	v_mfma_f32_16x16x32_bf16 v[120:123], v[132:135], v[24:27], v[120:123]
	v_exp_f32_e32 v227, v227
	v_exp_f32_e32 v228, v228
	v_exp_f32_e32 v229, v229
	v_mfma_f32_16x16x32_bf16 v[124:127], v[144:147], v[8:11], v[124:127]
	v_exp_f32_e32 v116, v116
	v_exp_f32_e32 v117, v117
	s_nop 1
	v_exp_f32_e32 v120, v120
	v_mfma_f32_16x16x32_bf16 v[222:225], v[156:159], v[24:27], v[222:225]
	v_exp_f32_e32 v121, v121
	s_nop 0
	v_exp_f32_e32 v175, v124
	v_exp_f32_e32 v177, v125
	v_mfma_f32_16x16x32_bf16 v[230:233], v[160:163], v[24:27], v[230:233]
	v_cvt_pk_bf16_f32 v125, v118, v119
	v_cvt_pk_bf16_f32 v118, v226, v227
	v_cvt_pk_bf16_f32 v119, v228, v229
	v_mfma_f32_16x16x32_bf16 v[128:131], v[144:147], v[24:27], v[128:131]
	v_exp_f32_e32 v122, v122
	v_exp_f32_e32 v123, v123
	v_exp_f32_e32 v222, v222
	v_exp_f32_e32 v223, v223
	v_exp_f32_e32 v224, v224
	v_exp_f32_e32 v225, v225
	v_exp_f32_e32 v226, v230
	v_exp_f32_e32 v227, v231
	v_exp_f32_e32 v228, v232
	v_exp_f32_e32 v229, v233
	v_exp_f32_e32 v221, v126
	v_cvt_pk_bf16_f32 v124, v116, v117
	v_cvt_pk_bf16_f32 v126, v175, v177
	v_cvt_pk_bf16_f32 v116, v234, v235
	v_cvt_pk_bf16_f32 v117, v236, v237
	v_exp_f32_e32 v175, v128
	v_exp_f32_e32 v177, v129
	v_cvt_pk_bf16_f32 v128, v120, v121
	v_cvt_pk_bf16_f32 v129, v122, v123
	v_cvt_pk_bf16_f32 v120, v222, v223
	v_cvt_pk_bf16_f32 v121, v224, v225
	v_cvt_pk_bf16_f32 v122, v226, v227
	v_cvt_pk_bf16_f32 v123, v228, v229
	v_mfma_f32_16x16x32_bf16 v[222:225], v[136:139], v[28:31], v[44:47]
	v_exp_f32_e32 v127, v127
	v_exp_f32_e32 v131, v131
	v_cvt_pk_bf16_f32 v127, v221, v127
	v_mfma_f32_16x16x32_bf16 v[136:139], v[136:139], v[36:39], v[44:47]
	v_exp_f32_e32 v221, v130
	v_cvt_pk_bf16_f32 v130, v175, v177
	v_cvt_pk_bf16_f32 v131, v221, v131
	v_mfma_f32_16x16x32_bf16 v[226:229], v[140:143], v[28:31], v[44:47]
	v_mfma_f32_16x16x32_bf16 v[140:143], v[140:143], v[36:39], v[44:47]
	v_mfma_f32_16x16x32_bf16 v[230:233], v[148:151], v[28:31], v[44:47]
	v_mfma_f32_16x16x32_bf16 v[148:151], v[148:151], v[36:39], v[44:47]
	v_mfma_f32_16x16x32_bf16 v[234:237], v[152:155], v[28:31], v[44:47]
	v_mfma_f32_16x16x32_bf16 v[152:155], v[152:155], v[36:39], v[44:47]
	v_mfma_f32_16x16x32_bf16 v[222:225], v[132:135], v[32:35], v[222:225]
	v_mfma_f32_16x16x32_bf16 v[136:139], v[132:135], v[40:43], v[136:139]
	v_mfma_f32_16x16x32_bf16 v[132:135], v[144:147], v[32:35], v[226:229]
	v_mfma_f32_16x16x32_bf16 v[144:147], v[144:147], v[40:43], v[140:143]
	s_nop 5
	v_exp_f32_e32 v138, v138
	v_exp_f32_e32 v134, v134
	v_exp_f32_e32 v135, v135
	v_mfma_f32_16x16x32_bf16 v[140:143], v[156:159], v[32:35], v[230:233]
	v_exp_f32_e32 v139, v139
	v_exp_f32_e32 v136, v136
	v_exp_f32_e32 v137, v137
	v_mfma_f32_16x16x32_bf16 v[148:151], v[156:159], v[40:43], v[148:151]
	v_exp_f32_e32 v132, v132
	v_exp_f32_e32 v133, v133
	v_exp_f32_e32 v147, v147
	v_mfma_f32_16x16x32_bf16 v[156:159], v[160:163], v[32:35], v[234:237]
	v_exp_f32_e32 v175, v140
	s_nop 2
	v_exp_f32_e32 v148, v148
	v_exp_f32_e32 v149, v149
	v_mfma_f32_16x16x32_bf16 v[152:155], v[160:163], v[40:43], v[152:155]
	v_exp_f32_e32 v150, v150
	v_exp_f32_e32 v156, v156
	v_exp_f32_e32 v157, v157
	v_exp_f32_e32 v151, v151
	v_exp_f32_e32 v160, v222
	s_nop 2
	v_exp_f32_e32 v154, v154
	v_exp_f32_e32 v155, v155
	v_exp_f32_e32 v222, v143
	v_cvt_pk_bf16_f32 v143, v134, v135
	v_cvt_pk_bf16_f32 v134, v156, v157
	v_exp_f32_e32 v157, v145
	v_cvt_pk_bf16_f32 v145, v138, v139
	v_cvt_pk_bf16_f32 v139, v154, v155
	v_add_u32_e32 v154, 0x2000, v173
	v_exp_f32_e32 v158, v158
	v_exp_f32_e32 v159, v159
	v_exp_f32_e32 v156, v144
	v_cvt_pk_bf16_f32 v144, v136, v137
	v_cvt_pk_bf16_f32 v136, v148, v149
	v_cvt_pk_bf16_f32 v137, v150, v151
	ds_read2_b64 v[148:151], v154 offset0:128 offset1:132
	v_exp_f32_e32 v161, v223
	v_exp_f32_e32 v162, v224
	v_exp_f32_e32 v163, v225
	v_cvt_pk_bf16_f32 v135, v158, v159
	v_exp_f32_e32 v158, v146
	v_exp_f32_e32 v152, v152
	v_exp_f32_e32 v153, v153
	v_exp_f32_e32 v177, v141
	v_exp_f32_e32 v221, v142
	v_cvt_pk_bf16_f32 v140, v160, v161
	v_cvt_pk_bf16_f32 v141, v162, v163
	v_cvt_pk_bf16_f32 v142, v132, v133
	v_cvt_pk_bf16_f32 v146, v156, v157
	v_cvt_pk_bf16_f32 v147, v158, v147
	s_waitcnt lgkmcnt(0)
	v_mfma_f32_16x16x32_bf16 v[112:115], v[148:151], v[124:127], v[112:115]
	v_cvt_pk_bf16_f32 v138, v152, v153
	v_add_u32_e32 v155, 0x3800, v173
	v_add_u32_e32 v156, 0x4800, v173
	v_mfma_f32_16x16x32_bf16 v[108:111], v[148:151], v[128:131], v[108:111]
	v_cvt_pk_bf16_f32 v132, v175, v177
	v_cvt_pk_bf16_f32 v133, v221, v222
	v_lshlrev_b64 v[222:223], 8, v[188:189]
	v_lshl_add_u64 v[222:223], v[178:179], 0, v[222:223]
	v_lshl_add_u64 v[226:227], v[190:191], 0, v[182:183]
	global_load_dwordx4 v[222:225], v[222:223], off
	v_lshlrev_b64 v[230:231], 8, v[186:187]
	global_load_dwordx4 v[226:229], v[226:227], off
	v_lshl_add_u64 v[230:231], v[178:179], 0, v[230:231]
	v_lshl_add_u64 v[234:235], v[190:191], 0, v[184:185]
	global_load_dwordx4 v[230:233], v[230:231], off
	global_load_dwordx4 v[234:237], v[234:235], off
	v_mfma_f32_16x16x32_bf16 v[100:103], v[148:151], v[140:143], v[100:103]
	v_mfma_f32_16x16x32_bf16 v[80:83], v[148:151], v[144:147], v[80:83]
	v_add_u32_e32 v148, 0x2800, v173
	ds_read2_b64 v[150:153], v148 offset0:160 offset1:164
	v_add_u32_e32 v149, 0x3000, v173
	s_waitcnt lgkmcnt(0)
; __device__ __forceinline__ f32x4 mfma16(bf16x8 a, bf16x8 b, f32x4 c) { return __builtin_amdgcn_mfma_f32_16x16x32_bf16(a, b, c, 0, 0, 0); }
; __device__ __forceinline__ void attn_item(CParams& p, int j2, int b, int h, int q0row, int nkeys, bf16_t* smem) {
;     ...
; #pragma unroll
;         for (int ksp = 0; ksp < 2; ++ksp)
; #pragma unroll
;             for (int d = 0; d < 5; ++d) {
;                 const bf16_t* vp = sV + (d * 16 + l16) * GST + ksp * 32 + quad * 4;
;                 const bf16x8 vf = lds8x2(vp, vp + 16);
; #pragma unroll
;                 for (int i = 0; i < 4; ++i) o[d][i] = mfma16(vf, pf[ksp][i], o[d][i]);
;             }
	v_mfma_f32_16x16x32_bf16 v[96:99], v[150:153], v[124:127], v[96:99]
	v_mfma_f32_16x16x32_bf16 v[76:79], v[150:153], v[128:131], v[76:79]
	v_mfma_f32_16x16x32_bf16 v[60:63], v[150:153], v[140:143], v[60:63]
	v_mfma_f32_16x16x32_bf16 v[20:23], v[150:153], v[144:147], v[20:23]
	ds_read2_b64 v[150:153], v149 offset0:192 offset1:196
	s_waitcnt lgkmcnt(0)
	v_mfma_f32_16x16x32_bf16 v[88:91], v[150:153], v[124:127], v[88:91]
	v_mfma_f32_16x16x32_bf16 v[68:71], v[150:153], v[128:131], v[68:71]
	v_mfma_f32_16x16x32_bf16 v[52:55], v[150:153], v[140:143], v[52:55]
	v_mfma_f32_16x16x32_bf16 v[0:3], v[150:153], v[144:147], v[0:3]
	ds_read2_b64 v[150:153], v155 offset0:224 offset1:228
	s_waitcnt lgkmcnt(0)
	v_mfma_f32_16x16x32_bf16 v[92:95], v[150:153], v[124:127], v[92:95]
	v_mfma_f32_16x16x32_bf16 v[72:75], v[150:153], v[128:131], v[72:75]
	v_mfma_f32_16x16x32_bf16 v[56:59], v[150:153], v[140:143], v[56:59]
	v_mfma_f32_16x16x32_bf16 v[16:19], v[150:153], v[144:147], v[16:19]
	ds_read2_b64 v[150:153], v156 offset1:4
	s_waitcnt lgkmcnt(0)
	v_mfma_f32_16x16x32_bf16 v[104:107], v[150:153], v[124:127], v[104:107]
	ds_read2_b64 v[124:127], v154 offset0:136 offset1:140
	s_waitcnt lgkmcnt(0)
	v_mfma_f32_16x16x32_bf16 v[112:115], v[124:127], v[116:119], v[112:115]
	v_mfma_f32_16x16x32_bf16 v[108:111], v[124:127], v[120:123], v[108:111]
	v_mfma_f32_16x16x32_bf16 v[100:103], v[124:127], v[132:135], v[100:103]
	v_mfma_f32_16x16x32_bf16 v[80:83], v[124:127], v[136:139], v[80:83]
	ds_read2_b64 v[124:127], v148 offset0:168 offset1:172
	s_waitcnt lgkmcnt(0)
	v_mfma_f32_16x16x32_bf16 v[96:99], v[124:127], v[116:119], v[96:99]
	v_mfma_f32_16x16x32_bf16 v[76:79], v[124:127], v[120:123], v[76:79]
	v_mfma_f32_16x16x32_bf16 v[60:63], v[124:127], v[132:135], v[60:63]
	v_mfma_f32_16x16x32_bf16 v[20:23], v[124:127], v[136:139], v[20:23]
	ds_read2_b64 v[124:127], v149 offset0:200 offset1:204
	s_waitcnt lgkmcnt(0)
	v_mfma_f32_16x16x32_bf16 v[88:91], v[124:127], v[116:119], v[88:91]
	v_mfma_f32_16x16x32_bf16 v[68:71], v[124:127], v[120:123], v[68:71]
	v_mfma_f32_16x16x32_bf16 v[52:55], v[124:127], v[132:135], v[52:55]
	v_mfma_f32_16x16x32_bf16 v[0:3], v[124:127], v[136:139], v[0:3]
	ds_read2_b64 v[124:127], v155 offset0:232 offset1:236
	s_waitcnt lgkmcnt(0)
	v_mfma_f32_16x16x32_bf16 v[92:95], v[124:127], v[116:119], v[92:95]
	v_mfma_f32_16x16x32_bf16 v[72:75], v[124:127], v[120:123], v[72:75]
	v_mfma_f32_16x16x32_bf16 v[56:59], v[124:127], v[132:135], v[56:59]
	v_mfma_f32_16x16x32_bf16 v[16:19], v[124:127], v[136:139], v[16:19]
	ds_read2_b64 v[124:127], v156 offset0:8 offset1:12
	v_mfma_f32_16x16x32_bf16 v[84:87], v[150:153], v[128:131], v[84:87]
	v_mfma_f32_16x16x32_bf16 v[64:67], v[150:153], v[140:143], v[64:67]
	v_mfma_f32_16x16x32_bf16 v[48:51], v[150:153], v[144:147], v[48:51]
	s_waitcnt lgkmcnt(0)
	v_mfma_f32_16x16x32_bf16 v[104:107], v[124:127], v[116:119], v[104:107]
	v_mfma_f32_16x16x32_bf16 v[84:87], v[124:127], v[120:123], v[84:87]
	v_mfma_f32_16x16x32_bf16 v[64:67], v[124:127], v[132:135], v[64:67]
	v_mfma_f32_16x16x32_bf16 v[48:51], v[124:127], v[136:139], v[48:51]
	s_cbranch_scc1 .LBB0_179
; __device__ __forceinline__ void attn_item(CParams& p, int j2, int b, int h, int q0row, int nkeys, bf16_t* smem) {
;     ...
;     bf16_t* as = (bf16_t*)(p.ws + WS_AS);
; #pragma unroll
;     for (int i = 0; i < 4; ++i) {
;         const float l = __shfl(o[4][i][0], l16);
;         const float inv = 1.f / l;
;         const int row = q0row + wave * 64 + i * 16 + l16;
; #pragma unroll
;         for (int d = 0; d < 4; ++d)
;             st4bf(as + frag_off(row, h * 64 + d * 16 + quad * 4, 1024), o[d][i][0] * inv, o[d][i][1] * inv, o[d][i][2] * inv, o[d][i][3] * inv);
;     }
	s_waitcnt vmcnt(0)
	v_and_or_b32 v4, v197, 64, v220
	v_lshlrev_b32_e32 v14, 2, v4
	s_nop 1
	ds_bpermute_b32 v4, v14, v104
	v_and_or_b32 v7, v169, 16, v220
	s_lshl_b32 s78, s8, 11
	v_lshlrev_b32_e32 v164, 4, v7
	s_mov_b32 s39, s0
	s_waitcnt lgkmcnt(0)
	v_div_scale_f32 v5, s[4:5], v4, v4, 1.0
	v_rcp_f32_e32 v6, v5
	s_nop 0
	v_fma_f32 v8, -v5, v6, 1.0
	v_fmac_f32_e32 v6, v8, v6
	v_div_scale_f32 v8, vcc, 1.0, v4, 1.0
	v_mul_f32_e32 v9, v8, v6
	v_fma_f32 v10, -v5, v9, v8
	v_fmac_f32_e32 v9, v10, v6
	v_fma_f32 v5, -v5, v9, v8
	v_div_fmas_f32 v5, v5, v6, v9
	v_div_fixup_f32 v6, v5, v4, 1.0
	v_ashrrev_i32_e32 v4, 4, v219
	v_ashrrev_i32_e32 v5, 31, v4
	v_lshlrev_b64 v[4:5], 15, v[4:5]
	v_lshl_add_u64 v[4:5], s[50:51], 0, v[4:5]
	v_lshl_add_u64 v[4:5], v[4:5], 0, s[78:79]
	v_lshl_add_u64 v[8:9], v[4:5], 0, v[164:165]
	v_and_b32_e32 v4, 8, v169
	v_mov_b32_e32 v5, v165
	v_pk_mul_f32 v[10:11], v[112:113], v[6:7] op_sel_hi:[1,0]
	v_pk_mul_f32 v[12:13], v[114:115], v[6:7] op_sel_hi:[1,0]
	v_lshl_add_u64 v[8:9], v[8:9], 0, v[4:5]
	v_cvt_pk_bf16_f32 v10, v10, v11
	v_cvt_pk_bf16_f32 v11, v12, v13
	global_store_dwordx2 v[8:9], v[10:11], off
	v_pk_mul_f32 v[10:11], v[96:97], v[6:7] op_sel_hi:[1,0]
	v_pk_mul_f32 v[12:13], v[98:99], v[6:7] op_sel_hi:[1,0]
	v_cvt_pk_bf16_f32 v10, v10, v11
	v_cvt_pk_bf16_f32 v11, v12, v13
	global_store_dwordx2 v[8:9], v[10:11], off offset:512
	v_pk_mul_f32 v[10:11], v[88:89], v[6:7] op_sel_hi:[1,0]
	v_pk_mul_f32 v[12:13], v[90:91], v[6:7] op_sel_hi:[1,0]
	v_cvt_pk_bf16_f32 v10, v10, v11
	v_cvt_pk_bf16_f32 v11, v12, v13
	global_store_dwordx2 v[8:9], v[10:11], off offset:1024
	v_pk_mul_f32 v[10:11], v[92:93], v[6:7] op_sel_hi:[1,0]
	v_pk_mul_f32 v[6:7], v[94:95], v[6:7] op_sel_hi:[1,0]
	v_cvt_pk_bf16_f32 v10, v10, v11
	v_cvt_pk_bf16_f32 v11, v6, v7
	ds_bpermute_b32 v6, v14, v84
	global_store_dwordx2 v[8:9], v[10:11], off offset:1536
	s_waitcnt lgkmcnt(0)
	v_div_scale_f32 v7, s[4:5], v6, v6, 1.0
	v_rcp_f32_e32 v8, v7
	s_nop 0
	v_fma_f32 v9, -v7, v8, 1.0
	v_fmac_f32_e32 v8, v9, v8
	v_div_scale_f32 v9, vcc, 1.0, v6, 1.0
	v_mul_f32_e32 v10, v9, v8
	v_fma_f32 v11, -v7, v10, v9
	v_fmac_f32_e32 v10, v11, v8
	v_fma_f32 v7, -v7, v10, v9
	v_div_fmas_f32 v7, v7, v8, v10
	v_ashrrev_i32_e32 v8, 4, v174
	v_ashrrev_i32_e32 v9, 31, v8
	v_lshlrev_b64 v[8:9], 15, v[8:9]
	v_lshl_add_u64 v[8:9], s[50:51], 0, v[8:9]
	v_div_fixup_f32 v6, v7, v6, 1.0
	v_lshl_add_u64 v[8:9], v[8:9], 0, s[78:79]
	v_lshl_add_u64 v[8:9], v[8:9], 0, v[164:165]
	v_pk_mul_f32 v[10:11], v[108:109], v[6:7] op_sel_hi:[1,0]
	v_pk_mul_f32 v[12:13], v[110:111], v[6:7] op_sel_hi:[1,0]
	v_lshl_add_u64 v[8:9], v[8:9], 0, v[4:5]
	v_cvt_pk_bf16_f32 v10, v10, v11
	v_cvt_pk_bf16_f32 v11, v12, v13
	global_store_dwordx2 v[8:9], v[10:11], off
	v_pk_mul_f32 v[10:11], v[76:77], v[6:7] op_sel_hi:[1,0]
	v_pk_mul_f32 v[12:13], v[78:79], v[6:7] op_sel_hi:[1,0]
	v_cvt_pk_bf16_f32 v10, v10, v11
	v_cvt_pk_bf16_f32 v11, v12, v13
	global_store_dwordx2 v[8:9], v[10:11], off offset:512
	v_pk_mul_f32 v[10:11], v[68:69], v[6:7] op_sel_hi:[1,0]
	v_pk_mul_f32 v[12:13], v[70:71], v[6:7] op_sel_hi:[1,0]
	v_cvt_pk_bf16_f32 v10, v10, v11
	v_cvt_pk_bf16_f32 v11, v12, v13
	global_store_dwordx2 v[8:9], v[10:11], off offset:1024
	v_pk_mul_f32 v[10:11], v[72:73], v[6:7] op_sel_hi:[1,0]
	v_pk_mul_f32 v[6:7], v[74:75], v[6:7] op_sel_hi:[1,0]
	v_cvt_pk_bf16_f32 v10, v10, v11
	v_cvt_pk_bf16_f32 v11, v6, v7
	ds_bpermute_b32 v6, v14, v64
	global_store_dwordx2 v[8:9], v[10:11], off offset:1536
	s_waitcnt lgkmcnt(0)
	v_div_scale_f32 v7, s[4:5], v6, v6, 1.0
	v_rcp_f32_e32 v8, v7
	s_nop 0
	v_fma_f32 v9, -v7, v8, 1.0
	v_fmac_f32_e32 v8, v9, v8
	v_div_scale_f32 v9, vcc, 1.0, v6, 1.0
	v_mul_f32_e32 v10, v9, v8
	v_fma_f32 v11, -v7, v10, v9
	v_fmac_f32_e32 v10, v11, v8
	v_fma_f32 v7, -v7, v10, v9
	v_div_fmas_f32 v7, v7, v8, v10
	v_ashrrev_i32_e32 v8, 4, v172
	v_ashrrev_i32_e32 v9, 31, v8
	v_lshlrev_b64 v[8:9], 15, v[8:9]
	v_lshl_add_u64 v[8:9], s[50:51], 0, v[8:9]
	v_div_fixup_f32 v6, v7, v6, 1.0
	v_lshl_add_u64 v[8:9], v[8:9], 0, s[78:79]
	v_lshl_add_u64 v[8:9], v[8:9], 0, v[164:165]
	v_pk_mul_f32 v[10:11], v[100:101], v[6:7] op_sel_hi:[1,0]
	v_pk_mul_f32 v[12:13], v[102:103], v[6:7] op_sel_hi:[1,0]
	v_lshl_add_u64 v[8:9], v[8:9], 0, v[4:5]
	v_cvt_pk_bf16_f32 v10, v10, v11
	v_cvt_pk_bf16_f32 v11, v12, v13
	global_store_dwordx2 v[8:9], v[10:11], off
	v_pk_mul_f32 v[10:11], v[60:61], v[6:7] op_sel_hi:[1,0]
	v_pk_mul_f32 v[12:13], v[62:63], v[6:7] op_sel_hi:[1,0]
	v_cvt_pk_bf16_f32 v10, v10, v11
	v_cvt_pk_bf16_f32 v11, v12, v13
	global_store_dwordx2 v[8:9], v[10:11], off offset:512
	v_pk_mul_f32 v[10:11], v[52:53], v[6:7] op_sel_hi:[1,0]
	v_pk_mul_f32 v[12:13], v[54:55], v[6:7] op_sel_hi:[1,0]
	v_cvt_pk_bf16_f32 v10, v10, v11
	v_cvt_pk_bf16_f32 v11, v12, v13
	global_store_dwordx2 v[8:9], v[10:11], off offset:1024
	v_pk_mul_f32 v[10:11], v[56:57], v[6:7] op_sel_hi:[1,0]
	v_pk_mul_f32 v[6:7], v[58:59], v[6:7] op_sel_hi:[1,0]
	v_cvt_pk_bf16_f32 v10, v10, v11
	v_cvt_pk_bf16_f32 v11, v6, v7
	ds_bpermute_b32 v6, v14, v48
	global_store_dwordx2 v[8:9], v[10:11], off offset:1536
	s_waitcnt lgkmcnt(0)
	v_div_scale_f32 v7, s[4:5], v6, v6, 1.0
	v_rcp_f32_e32 v8, v7
	s_nop 0
	v_fma_f32 v9, -v7, v8, 1.0
	v_fmac_f32_e32 v8, v9, v8
	v_div_scale_f32 v9, vcc, 1.0, v6, 1.0
	v_mul_f32_e32 v10, v9, v8
	v_fma_f32 v11, -v7, v10, v9
	v_fmac_f32_e32 v10, v11, v8
	v_fma_f32 v7, -v7, v10, v9
	v_div_fmas_f32 v7, v7, v8, v10
	v_ashrrev_i32_e32 v8, 4, v170
	v_ashrrev_i32_e32 v9, 31, v8
	v_lshlrev_b64 v[8:9], 15, v[8:9]
	v_lshl_add_u64 v[8:9], s[50:51], 0, v[8:9]
	v_lshl_add_u64 v[8:9], v[8:9], 0, s[78:79]
	v_div_fixup_f32 v6, v7, v6, 1.0
	v_lshl_add_u64 v[8:9], v[8:9], 0, v[164:165]
	v_lshl_add_u64 v[4:5], v[8:9], 0, v[4:5]
	v_pk_mul_f32 v[8:9], v[80:81], v[6:7] op_sel_hi:[1,0]
	v_pk_mul_f32 v[10:11], v[82:83], v[6:7] op_sel_hi:[1,0]
	v_pk_mul_f32 v[0:1], v[0:1], v[6:7] op_sel_hi:[1,0]
	v_pk_mul_f32 v[2:3], v[2:3], v[6:7] op_sel_hi:[1,0]
	v_cvt_pk_bf16_f32 v8, v8, v9
	v_cvt_pk_bf16_f32 v9, v10, v11
	v_cvt_pk_bf16_f32 v0, v0, v1
	v_cvt_pk_bf16_f32 v1, v2, v3
	global_store_dwordx2 v[4:5], v[8:9], off
	v_pk_mul_f32 v[8:9], v[20:21], v[6:7] op_sel_hi:[1,0]
	v_pk_mul_f32 v[10:11], v[22:23], v[6:7] op_sel_hi:[1,0]
	global_store_dwordx2 v[4:5], v[0:1], off offset:1024
	v_pk_mul_f32 v[0:1], v[16:17], v[6:7] op_sel_hi:[1,0]
	v_pk_mul_f32 v[2:3], v[18:19], v[6:7] op_sel_hi:[1,0]
	v_cvt_pk_bf16_f32 v8, v8, v9
	v_cvt_pk_bf16_f32 v9, v10, v11
	v_cvt_pk_bf16_f32 v0, v0, v1
	v_cvt_pk_bf16_f32 v1, v2, v3
	global_store_dwordx2 v[4:5], v[8:9], off offset:512
	global_store_dwordx2 v[4:5], v[0:1], off offset:1536
	s_branch .LBB0_166
